# prep S1: short-conv weight loads of all taps issued up front (one latency round)
# baseline (speedup 1.0000x reference)
.LBB0_348:
	s_mul_hi_i32 s28, s54, 0x2aaaaaab
	s_lshr_b32 s29, s28, 31
	s_add_i32 s22, s28, s29
	s_ashr_i32 s2, s22, 31
	s_lshr_b32 s2, s2, 27
	s_add_i32 s2, s22, s2
	v_mov_b32_e32 v80, v225
	s_and_b32 s2, s2, 0x3ffffe0
	s_sub_i32 s2, s22, s2
	v_lshlrev_b32_e32 v0, 3, v80
	s_lshl_b32 s23, s2, 6
	v_and_b32_e32 v14, 56, v0
	s_mul_i32 s2, s22, 0x180
	v_ashrrev_i32_e32 v58, 3, v80
	v_subrev_u32_e32 v0, s2, v14
	v_add_u32_e32 v0, s53, v0
	v_add_u32_e32 v12, s23, v58
	v_add_u32_e32 v2, -1, v12
	v_ashrrev_i32_e32 v1, 31, v0
	s_movk_i32 s2, 0x800
	v_mov_b32_e32 v10, 0
	v_lshl_add_u64 v[0:1], v[0:1], 2, s[0:1]
	s_mov_b64 s[4:5], 0x1200
	v_lshl_add_u64 v[218:219], v[0:1], 0, s[4:5]
	s_mov_b64 s[4:5], 0x2400
	v_lshl_add_u64 v[244:245], v[0:1], 0, s[4:5]
	global_load_dwordx4 v[154:157], v[218:219], off
	global_load_dwordx4 v[158:161], v[218:219], off offset:16
	global_load_dwordx4 v[162:165], v[244:245], off
	global_load_dwordx4 v[166:169], v[244:245], off offset:16
	global_load_dwordx4 v[170:173], v[0:1], off offset:1536
	global_load_dwordx4 v[174:177], v[0:1], off offset:1552
	global_load_dwordx4 v[178:181], v[218:219], off offset:1536
	global_load_dwordx4 v[182:185], v[218:219], off offset:1552
	global_load_dwordx4 v[186:189], v[244:245], off offset:1536
	global_load_dwordx4 v[190:193], v[244:245], off offset:1552
	global_load_dwordx4 v[194:197], v[0:1], off offset:3072
	global_load_dwordx4 v[198:201], v[0:1], off offset:3088
	global_load_dwordx4 v[202:205], v[218:219], off offset:3072
	global_load_dwordx4 v[206:209], v[218:219], off offset:3088
	global_load_dwordx4 v[210:213], v[244:245], off offset:3072
	global_load_dwordx4 v[226:229], v[244:245], off offset:3088
	v_cmp_gt_u32_e64 s[42:43], s2, v2
	v_mov_b32_e32 v11, 0
	v_mov_b32_e32 v2, 0
	v_mov_b32_e32 v3, 0
	v_mov_b32_e32 v4, 0
	v_mov_b32_e32 v5, v10
	v_mov_b32_e32 v6, v10
	v_mov_b32_e32 v7, v10
	v_mov_b32_e32 v8, 0
	v_mov_b32_e32 v9, 0
	s_and_saveexec_b64 s[2:3], s[42:43]
	s_cbranch_execz .LBB0_350
	global_load_dwordx4 v[6:9], v[0:1], off offset:16
	global_load_dwordx4 v[2:5], v[0:1], off
	s_waitcnt vmcnt(10)
	v_lshlrev_b32_e32 v10, 16, v16
	v_and_b32_e32 v11, 0xffff0000, v16
	s_waitcnt vmcnt(0)
	v_pk_fma_f32 v[2:3], v[2:3], v[10:11], 0 op_sel_hi:[1,1,0]
	v_lshlrev_b32_e32 v10, 16, v18
	v_and_b32_e32 v11, 0xffff0000, v18
	v_pk_fma_f32 v[6:7], v[6:7], v[10:11], 0 op_sel_hi:[1,1,0]
	v_lshlrev_b32_e32 v10, 16, v17
	v_and_b32_e32 v11, 0xffff0000, v17
	v_pk_fma_f32 v[4:5], v[4:5], v[10:11], 0 op_sel_hi:[1,1,0]
	v_lshlrev_b32_e32 v10, 16, v19
	v_and_b32_e32 v11, 0xffff0000, v19
	v_pk_fma_f32 v[10:11], v[8:9], v[10:11], 0 op_sel_hi:[1,1,0]
	s_nop 0
	v_mov_b32_e32 v8, v10
	v_mov_b32_e32 v9, v11
.LBB0_350:
	s_or_b64 exec, exec, s[2:3]
	s_movk_i32 s2, 0x800
	v_cmp_gt_u32_e64 s[44:45], s2, v12
	s_and_saveexec_b64 s[2:3], s[44:45]
	s_cbranch_execz .LBB0_352
	v_add_co_u32_e32 v52, vcc, 0x1000, v0
	s_mov_b64 s[4:5], 0x1200
	s_nop 0
	v_addc_co_u32_e32 v53, vcc, 0, v1, vcc
	v_lshl_add_u64 v[8:9], v[0:1], 0, s[4:5]
	s_nop 0
	s_waitcnt vmcnt(6)
	v_lshlrev_b32_e32 v8, 16, v40
	v_and_b32_e32 v9, 0xffff0000, v40
	s_waitcnt vmcnt(1)
	v_pk_fma_f32 v[2:3], v[154:155], v[8:9], v[2:3]
	v_lshlrev_b32_e32 v8, 16, v42
	v_and_b32_e32 v9, 0xffff0000, v42
	s_waitcnt vmcnt(0)
	v_pk_fma_f32 v[6:7], v[158:159], v[8:9], v[6:7]
	v_lshlrev_b32_e32 v8, 16, v41
	v_and_b32_e32 v9, 0xffff0000, v41
	v_pk_fma_f32 v[4:5], v[156:157], v[8:9], v[4:5]
	v_lshlrev_b32_e32 v8, 16, v43
	v_and_b32_e32 v9, 0xffff0000, v43
	v_pk_fma_f32 v[8:9], v[160:161], v[8:9], v[10:11]
.LBB0_352:
	s_or_b64 exec, exec, s[2:3]
	v_add_u32_e32 v10, 1, v12
	s_movk_i32 s2, 0x800
	v_cmp_gt_u32_e64 s[46:47], s2, v10
	s_and_saveexec_b64 s[2:3], s[46:47]
	s_cbranch_execz .LBB0_354
	s_mov_b64 s[4:5], 0x2400
	v_add_co_u32_e32 v10, vcc, 0x2000, v0
	v_lshl_add_u64 v[52:53], v[0:1], 0, s[4:5]
	s_nop 0
	v_addc_co_u32_e32 v11, vcc, 0, v1, vcc
	s_nop 0
	s_waitcnt vmcnt(6)
	v_lshlrev_b32_e32 v56, 16, v24
	v_and_b32_e32 v57, 0xffff0000, v24
	s_waitcnt vmcnt(1)
	v_pk_fma_f32 v[2:3], v[162:163], v[56:57], v[2:3]
	v_lshlrev_b32_e32 v10, 16, v26
	v_and_b32_e32 v11, 0xffff0000, v26
	s_waitcnt vmcnt(0)
	v_pk_fma_f32 v[6:7], v[166:167], v[10:11], v[6:7]
	v_lshlrev_b32_e32 v10, 16, v25
	v_and_b32_e32 v11, 0xffff0000, v25
	v_pk_fma_f32 v[4:5], v[164:165], v[10:11], v[4:5]
	v_lshlrev_b32_e32 v10, 16, v27
	v_and_b32_e32 v11, 0xffff0000, v27
	v_pk_fma_f32 v[8:9], v[168:169], v[10:11], v[8:9]

.LBB0_357:
	s_mov_b64 s[4:5], 0x2a00
	v_add_co_u32_e32 v10, vcc, 0x2000, v0
	v_lshl_add_u64 v[52:53], v[0:1], 0, s[4:5]
	s_nop 0
	v_addc_co_u32_e32 v11, vcc, 0, v1, vcc
	s_nop 0
	s_waitcnt vmcnt(7)
	v_lshlrev_b32_e32 v56, 16, v28
	v_and_b32_e32 v57, 0xffff0000, v28
	s_waitcnt vmcnt(1)
	v_pk_fma_f32 v[8:9], v[186:187], v[56:57], v[8:9]
	v_lshlrev_b32_e32 v10, 16, v30
	v_and_b32_e32 v11, 0xffff0000, v30
	s_waitcnt vmcnt(0)
	v_pk_fma_f32 v[2:3], v[190:191], v[10:11], v[2:3]
	v_lshlrev_b32_e32 v10, 16, v29
	v_and_b32_e32 v11, 0xffff0000, v29
	v_pk_fma_f32 v[6:7], v[188:189], v[10:11], v[6:7]
	v_lshlrev_b32_e32 v10, 16, v31
	v_and_b32_e32 v11, 0xffff0000, v31
	v_pk_fma_f32 v[4:5], v[192:193], v[10:11], v[4:5]

.LBB0_361:
	s_mov_b64 s[4:5], 0x3000
	v_lshl_add_u64 v[10:11], v[0:1], 0, s[4:5]
	v_add_co_u32_e32 v0, vcc, 0x3000, v0
	s_nop 1
	v_addc_co_u32_e32 v1, vcc, 0, v1, vcc
	s_waitcnt vmcnt(2)
	v_lshlrev_b32_e32 v0, 16, v44
	v_and_b32_e32 v1, 0xffff0000, v44
	s_waitcnt vmcnt(1)
	v_pk_fma_f32 v[8:9], v[210:211], v[0:1], v[8:9]
	v_lshlrev_b32_e32 v0, 16, v46
	v_and_b32_e32 v1, 0xffff0000, v46
	s_waitcnt vmcnt(0)
	v_pk_fma_f32 v[2:3], v[226:227], v[0:1], v[2:3]
	v_lshlrev_b32_e32 v0, 16, v45
	v_and_b32_e32 v1, 0xffff0000, v45
	v_pk_fma_f32 v[6:7], v[212:213], v[0:1], v[6:7]
	v_lshlrev_b32_e32 v0, 16, v47
	v_and_b32_e32 v1, 0xffff0000, v47
	v_pk_fma_f32 v[4:5], v[228:229], v[0:1], v[4:5]

.LBB0_552:
	s_waitcnt vmcnt(9)
	v_lshlrev_b32_e32 v6, 16, v20
	v_and_b32_e32 v7, 0xffff0000, v20
	s_waitcnt vmcnt(0)
	v_pk_fma_f32 v[8:9], v[170:171], v[6:7], 0 op_sel_hi:[1,1,0]
	v_lshlrev_b32_e32 v6, 16, v22
	v_and_b32_e32 v7, 0xffff0000, v22
	v_pk_fma_f32 v[2:3], v[174:175], v[6:7], 0 op_sel_hi:[1,1,0]
	v_lshlrev_b32_e32 v6, 16, v21
	v_and_b32_e32 v7, 0xffff0000, v21
	v_pk_fma_f32 v[6:7], v[172:173], v[6:7], 0 op_sel_hi:[1,1,0]
	v_lshlrev_b32_e32 v10, 16, v23
	v_and_b32_e32 v11, 0xffff0000, v23
	v_pk_fma_f32 v[10:11], v[176:177], v[10:11], 0 op_sel_hi:[1,1,0]
	s_nop 0
	v_mov_b32_e32 v4, v10
	v_mov_b32_e32 v5, v11
	s_or_b64 exec, exec, s[2:3]
	s_and_saveexec_b64 s[2:3], s[44:45]
	s_cbranch_execz .LBB0_356
.LBB0_553:
	v_add_co_u32_e32 v12, vcc, 0x1000, v0
	s_mov_b64 s[4:5], 0x1800
	s_nop 0
	v_addc_co_u32_e32 v13, vcc, 0, v1, vcc
	v_lshl_add_u64 v[4:5], v[0:1], 0, s[4:5]
	s_waitcnt vmcnt(4)
	v_lshlrev_b32_e32 v4, 16, v48
	v_and_b32_e32 v5, 0xffff0000, v48
	s_waitcnt vmcnt(1)
	v_pk_fma_f32 v[8:9], v[178:179], v[4:5], v[8:9]
	v_lshlrev_b32_e32 v4, 16, v50
	v_and_b32_e32 v5, 0xffff0000, v50
	s_waitcnt vmcnt(0)
	v_pk_fma_f32 v[2:3], v[182:183], v[4:5], v[2:3]
	v_lshlrev_b32_e32 v4, 16, v49
	v_and_b32_e32 v5, 0xffff0000, v49
	v_pk_fma_f32 v[6:7], v[180:181], v[4:5], v[6:7]
	v_lshlrev_b32_e32 v4, 16, v51
	v_and_b32_e32 v5, 0xffff0000, v51
	v_pk_fma_f32 v[4:5], v[184:185], v[4:5], v[10:11]
	s_or_b64 exec, exec, s[2:3]
	s_and_saveexec_b64 s[2:3], s[46:47]
	s_cbranch_execnz .LBB0_357
	s_branch .LBB0_358
.LBB0_554:
	s_waitcnt vmcnt(5)
	v_lshlrev_b32_e32 v6, 16, v32
	v_and_b32_e32 v7, 0xffff0000, v32
	s_waitcnt vmcnt(0)
	v_pk_fma_f32 v[8:9], v[194:195], v[6:7], 0 op_sel_hi:[1,1,0]
	v_lshlrev_b32_e32 v6, 16, v34
	v_and_b32_e32 v7, 0xffff0000, v34
	v_pk_fma_f32 v[2:3], v[198:199], v[6:7], 0 op_sel_hi:[1,1,0]
	v_lshlrev_b32_e32 v6, 16, v33
	v_and_b32_e32 v7, 0xffff0000, v33
	v_pk_fma_f32 v[6:7], v[196:197], v[6:7], 0 op_sel_hi:[1,1,0]
	v_lshlrev_b32_e32 v10, 16, v35
	v_and_b32_e32 v11, 0xffff0000, v35
	v_pk_fma_f32 v[10:11], v[200:201], v[10:11], 0 op_sel_hi:[1,1,0]
	s_nop 0
	v_mov_b32_e32 v4, v10
	v_mov_b32_e32 v5, v11
	s_or_b64 exec, exec, s[2:3]
	s_and_saveexec_b64 s[2:3], s[44:45]
	s_cbranch_execz .LBB0_360
.LBB0_555:
	v_add_co_u32_e32 v14, vcc, 0x1000, v0
	s_mov_b64 s[4:5], 0x1e00
	s_nop 0
	v_addc_co_u32_e32 v15, vcc, 0, v1, vcc
	v_lshl_add_u64 v[4:5], v[0:1], 0, s[4:5]
	s_waitcnt vmcnt(3)
	v_lshlrev_b32_e32 v4, 16, v36
	v_and_b32_e32 v5, 0xffff0000, v36
	s_waitcnt vmcnt(1)
	v_pk_fma_f32 v[8:9], v[202:203], v[4:5], v[8:9]
	v_lshlrev_b32_e32 v4, 16, v38
	v_and_b32_e32 v5, 0xffff0000, v38
	s_waitcnt vmcnt(0)
	v_pk_fma_f32 v[2:3], v[206:207], v[4:5], v[2:3]
	v_lshlrev_b32_e32 v4, 16, v37
	v_and_b32_e32 v5, 0xffff0000, v37
	v_pk_fma_f32 v[6:7], v[204:205], v[4:5], v[6:7]
	v_lshlrev_b32_e32 v4, 16, v39
	v_and_b32_e32 v5, 0xffff0000, v39
	v_pk_fma_f32 v[4:5], v[208:209], v[4:5], v[10:11]
	s_or_b64 exec, exec, s[2:3]
	s_and_saveexec_b64 s[2:3], s[46:47]
	s_cbranch_execnz .LBB0_361
	s_branch .LBB0_362
